# P4 fused epilogue first half: 16 x loads in flight + batched cross-lane reduce (on top of P0 unroll + LRU fwd MFMA operand prefetch)
# speedup vs baseline: 1.0064x; 1.0012x over previous
; template <int dir>
; __device__ __forceinline__ void lru_pass(LAS unsigned char* lds, const Params& P, int b, int h, int q, bool dry) {
;     ...
;                     for (int i = 0; i < 4; ++i) { const int id = tid + i * NTHREADS; *(u32x4*)(Hg + (size_t)(t0_prev + (id >> 3)) * DM + (id & 7) * 4) = *(const LAS u32x4*)(TOUT + (id >> 3) * IO_WP + (id & 7) * 16); }
;                 } else if (!dry) {
; #pragma unroll
;                     for (int i = 0; i < 2; ++i) { const int id = tid + i * NTHREADS; *(u32x4*)(Z + ZSLAB(8 + h, (size_t)b * SEQ + t0_prev + (id >> 2)) + q * 32 + (id & 3) * 8) = *(const LAS u32x4*)(TOUT + (id >> 2) * IO_NP + (id & 3) * 16); }
;                 }
;             }
;             f32x16 zr, zi;
; #pragma unroll
;             for (int v = 0; v < 16; ++v) { zr[v] = br; zi[v] = bi; }
;             const int sbase = 32 * wid + 16 * g;
;             { const int sl = 32 * wid + s_i; const int tlA = dir == 0 ? sl : 255 - sl;
;               const LAS unsigned char* ap = XC + tlA * XC_PITCH + 16 * g;
;               const LAS unsigned char* wrp = WB + nl * XC_PITCH + 16 * g; const LAS unsigned char* wip = wrp + 32 * XC_PITCH;
; #pragma unroll
;               for (int ks = 0; ks < 8; ++ks) { const bf16x8 A = *(const LAS bf16x8*)(ap + 32 * ks);
;                   const bf16x8 Br = *(const LAS bf16x8*)(wrp + 32 * ks), Bi = *(const LAS bf16x8*)(wip + 32 * ks);
;                   zr = __builtin_amdgcn_mfma_f32_32x32x16_bf16(A, Br, zr, 0, 0, 0); zi = __builtin_amdgcn_mfma_f32_32x32x16_bf16(A, Bi, zi, 0, 0, 0); } }
;             unsigned xcb[16], pk[16];
; #pragma unroll
;             for (int v = 0; v < 16; ++v) { const int s = sbase + v; const int tl = dir == 0 ? s : 255 - s; xcb[v] = *(const LAS bf16_t*)(XC + tl * XC_PITCH + chl * 2);
;                 if (dir == 0) pk[v] = *(const LAS bf16_t*)(TIN + tl * IO_NP + nl * 2); else pk[v] = *(const LAS unsigned*)(TIN + tl * IO_WP + nl * 4); }
;             float Pp = 1.f, E = 0.f;
; #pragma unroll
;             for (int v = 0; v < 16; ++v) {
;                 const float xcv = __uint_as_float(xcb[v] << 16);
;                 const float r = __builtin_amdgcn_rcpf(1.0f + __builtin_amdgcn_exp2f(zr[v]));
;                 const float ig = __builtin_amdgcn_rcpf(1.0f + __builtin_amdgcn_exp2f(zi[v]));
;                 const float a = __builtin_amdgcn_exp2f(cl * r);
.LBB0_295:
	s_waitcnt lgkmcnt(0)
	s_barrier
	s_cmp_lt_u32 s93, 2
	s_cbranch_scc1 .LBB0_297
	v_add_u32_e32 v48, v129, v149
	ds_read_b128 v[32:35], v48
	v_add_u32_e32 v48, v129, v146
	ds_read_b128 v[36:39], v48
	v_add_u32_e32 v48, v129, v144
	ds_read_b128 v[40:43], v48
	v_add_u32_e32 v48, v129, v142
	ds_read_b128 v[44:47], v48
	v_add_u32_e32 v48, s91, v148
	v_ashrrev_i32_e32 v49, 31, v48
	v_lshlrev_b64 v[48:49], 12, v[48:49]
	v_lshl_add_u64 v[48:49], v[130:131], 0, v[48:49]
	v_add_u32_e32 v50, s91, v145
	v_ashrrev_i32_e32 v51, 31, v50
	v_lshlrev_b64 v[50:51], 12, v[50:51]
	v_lshl_add_u64 v[50:51], v[130:131], 0, v[50:51]
	v_add_u32_e32 v52, s91, v143
	v_ashrrev_i32_e32 v53, 31, v52
	v_lshlrev_b64 v[52:53], 12, v[52:53]
	v_lshl_add_u64 v[52:53], v[130:131], 0, v[52:53]
	v_add_u32_e32 v54, s91, v141
	v_ashrrev_i32_e32 v55, 31, v54
	v_lshlrev_b64 v[54:55], 12, v[54:55]
	v_lshl_add_u64 v[54:55], v[130:131], 0, v[54:55]
	s_waitcnt lgkmcnt(3)
	global_store_dwordx4 v[48:49], v[32:35], off
	s_waitcnt lgkmcnt(2)
	global_store_dwordx4 v[50:51], v[36:39], off
	s_waitcnt lgkmcnt(1)
	global_store_dwordx4 v[52:53], v[40:43], off
	s_waitcnt lgkmcnt(0)
	global_store_dwordx4 v[54:55], v[44:47], off
.LBB0_297:
	s_cmp_lg_u32 s93, 0
	s_cbranch_scc1 .Llruf_wres
	ds_read_b128 v[204:207], v161
	ds_read_b128 v[208:211], v161 offset:32
	ds_read_b128 v[212:215], v161 offset:64
	ds_read_b128 v[216:219], v161 offset:96
	ds_read_b128 v[220:223], v161 offset:128
	ds_read_b128 v[224:227], v161 offset:160
	ds_read_b128 v[228:231], v161 offset:192
	ds_read_b128 v[232:235], v161 offset:224
	s_waitcnt lgkmcnt(0)
.Llruf_wres:
	ds_read_b128 v[120:123], v160
	ds_read_b128 v[124:127], v160 offset:32
	ds_read_b128 v[168:171], v160 offset:64
	ds_read_b128 v[172:175], v160 offset:96
	ds_read_b128 v[176:179], v160 offset:128
	ds_read_b128 v[180:183], v160 offset:160
	ds_read_b128 v[184:187], v160 offset:192
	ds_read_b128 v[188:191], v160 offset:224
	ds_read_b128 v[236:239], v161 offset:8704
	ds_read_b128 v[240:243], v161 offset:8736
	ds_read_b128 v[244:247], v161 offset:8768
	ds_read_b128 v[248:251], v161 offset:8800
	s_waitcnt lgkmcnt(11)
	v_mfma_f32_32x32x16_bf16 v[32:47], v[120:123], v[204:207], v[0:15]
	s_waitcnt lgkmcnt(10)
	v_mfma_f32_32x32x16_bf16 v[32:47], v[124:127], v[208:211], v[32:47]
	s_waitcnt lgkmcnt(9)
	v_mfma_f32_32x32x16_bf16 v[32:47], v[168:171], v[212:215], v[32:47]
	s_waitcnt lgkmcnt(8)
	v_mfma_f32_32x32x16_bf16 v[32:47], v[172:175], v[216:219], v[32:47]
	s_waitcnt lgkmcnt(7)
	v_mfma_f32_32x32x16_bf16 v[32:47], v[176:179], v[220:223], v[32:47]
	s_waitcnt lgkmcnt(6)
	v_mfma_f32_32x32x16_bf16 v[32:47], v[180:183], v[224:227], v[32:47]
	s_waitcnt lgkmcnt(5)
	v_mfma_f32_32x32x16_bf16 v[32:47], v[184:187], v[228:231], v[32:47]
	s_waitcnt lgkmcnt(4)
	v_mfma_f32_32x32x16_bf16 v[32:47], v[188:191], v[232:235], v[32:47]
	s_waitcnt lgkmcnt(3)
	v_mfma_f32_32x32x16_bf16 v[48:63], v[120:123], v[236:239], v[16:31]
	ds_read_b128 v[236:239], v161 offset:8832
	s_nop 8
	v_exp_f32_e32 v32, v32
	v_exp_f32_e32 v33, v33
	v_exp_f32_e32 v34, v34
	v_add_f32_e32 v32, 1.0, v32
	v_rcp_f32_e32 v32, v32
	s_waitcnt lgkmcnt(3)
	v_mfma_f32_32x32x16_bf16 v[48:63], v[124:127], v[240:243], v[48:63]
	ds_read_b128 v[240:243], v161 offset:8864
	v_add_f32_e32 v33, 1.0, v33
	v_mul_f32_e32 v32, v138, v32
	v_rcp_f32_e32 v33, v33
	s_nop 0
	v_mul_f32_e32 v33, v138, v33
	s_waitcnt lgkmcnt(3)
	v_mfma_f32_32x32x16_bf16 v[48:63], v[168:171], v[244:247], v[48:63]
	ds_read_b128 v[244:247], v161 offset:8896
	v_exp_f32_e32 v33, v33
	s_waitcnt lgkmcnt(3)
	v_mfma_f32_32x32x16_bf16 v[48:63], v[172:175], v[248:251], v[48:63]
	ds_read_b128 v[248:251], v161 offset:8928
	ds_read_u16 v152, v162
	ds_read_u16 v154, v162 offset:272
	ds_read_u16 v155, v162 offset:544
	ds_read_u16 v157, v162 offset:816
	ds_read_u16 v196, v162 offset:1088
	ds_read_u16 v197, v162 offset:1360
	s_waitcnt lgkmcnt(5)
	v_lshlrev_b32_e32 v152, 16, v152
	s_waitcnt lgkmcnt(4)
	v_lshlrev_b32_e32 v154, 16, v154
	v_mfma_f32_32x32x16_bf16 v[48:63], v[176:179], v[236:239], v[48:63]
	ds_read_u16 v177, v162 offset:1632
	ds_read_u16 v178, v162 offset:1904
	ds_read_u16 v127, v163
	ds_read_u16 v124, v163 offset:80
	ds_read_u16 v121, v163 offset:160
	ds_read_u16 v66, v163 offset:240
	ds_read_u16 v64, v163 offset:320
	ds_read_u16 v126, v163 offset:400
	ds_read_u16 v123, v163 offset:480
	ds_read_u16 v120, v163 offset:560
	v_mfma_f32_32x32x16_bf16 v[48:63], v[180:183], v[240:243], v[48:63]
	v_exp_f32_e32 v171, v32
	ds_read_u16 v179, v162 offset:2176
	ds_read_u16 v180, v162 offset:2448
	ds_read_u16 v181, v162 offset:2720
	v_mfma_f32_32x32x16_bf16 v[48:63], v[184:187], v[244:247], v[48:63]
	ds_read_u16 v182, v162 offset:2992
	ds_read_u16 v183, v162 offset:3264
	ds_read_u16 v184, v162 offset:3536
	ds_read_u16 v185, v162 offset:3808
	ds_read_u16 v187, v162 offset:4080
	v_mfma_f32_32x32x16_bf16 v[48:63], v[188:191], v[248:251], v[48:63]
	s_nop 11
	v_exp_f32_e32 v172, v48
	ds_read_u16 v170, v163 offset:640
	ds_read_u16 v169, v163 offset:720
	ds_read_u16 v168, v163 offset:800
	ds_read_u16 v166, v163 offset:880
	ds_read_u16 v125, v163 offset:960
	ds_read_u16 v122, v163 offset:1040
	ds_read_u16 v67, v163 offset:1120
	ds_read_u16 v48, v163 offset:1200
	v_add_f32_e32 v32, 1.0, v172
	v_fma_f32 v172, -v171, v171, 1.0
	v_rcp_f32_e32 v32, v32
	v_sqrt_f32_e32 v172, v172
	s_nop 0
	v_mul_f32_e32 v32, v172, v32
	v_exp_f32_e32 v172, v49
	v_mul_f32_e32 v49, v32, v152
	v_fma_f32 v152, -v33, v33, 1.0
	v_sqrt_f32_e32 v152, v152
	v_add_f32_e32 v32, 1.0, v172
	v_rcp_f32_e32 v32, v32
	v_fmac_f32_e32 v49, 0, v171
	v_mul_f32_e32 v32, v152, v32
	v_mul_f32_e32 v172, v32, v154
	v_add_f32_e32 v32, 1.0, v34
	v_rcp_f32_e32 v32, v32
	v_exp_f32_e32 v34, v50
	v_fmac_f32_e32 v172, v33, v49
	v_mul_f32_e32 v50, v171, v33
	v_mul_f32_e32 v32, v138, v32
	v_exp_f32_e32 v32, v32
	v_add_f32_e32 v33, 1.0, v34
	v_exp_f32_e32 v34, v35
	v_rcp_f32_e32 v33, v33
	v_fma_f32 v35, -v32, v32, 1.0
	v_sqrt_f32_e32 v35, v35
	v_add_f32_e32 v34, 1.0, v34
	v_rcp_f32_e32 v34, v34
	s_waitcnt lgkmcnt(14)
; template <int dir>
; __device__ __forceinline__ void lru_pass(LAS unsigned char* lds, const Params& P, int b, int h, int q, bool dry) {
;     ...
;             float Pp = 1.f, E = 0.f;
; #pragma unroll
;             for (int v = 0; v < 16; ++v) {
;                 const float xcv = __uint_as_float(xcb[v] << 16);
;                 const float r = __builtin_amdgcn_rcpf(1.0f + __builtin_amdgcn_exp2f(zr[v]));
;                 const float ig = __builtin_amdgcn_rcpf(1.0f + __builtin_amdgcn_exp2f(zi[v]));
;                 const float a = __builtin_amdgcn_exp2f(cl * r);
;                 const float sq = __builtin_amdgcn_sqrtf(fmaf(-a, a, 1.0f));
;                 const float u = sq * ig * xcv;
;                 E = fmaf(a, E, u); Pp *= a; zr[v] = E; zi[v] = Pp; }
;             const float Po = __shfl_xor(Pp, 32), Eo = __shfl_xor(E, 32);
;             const float P0 = g ? Po : Pp, E0 = g ? Eo : E, P1 = g ? Pp : Po, E1 = g ? E : Eo;
;             if (g == 0) { AGG[(wid * 2 + 0) * 32 + nl] = P0 * P1; AGG[(wid * 2 + 1) * 32 + nl] = fmaf(P1, E0, E1); }
	v_lshlrev_b32_e32 v152, 16, v155
	v_mul_f32_e32 v33, v35, v33
	v_mul_f32_e32 v173, v33, v152
	v_mul_f32_e32 v34, v138, v34
	v_exp_f32_e32 v33, v51
	v_exp_f32_e32 v34, v34
	v_fmac_f32_e32 v173, v32, v172
	v_mul_f32_e32 v51, v32, v50
	v_exp_f32_e32 v32, v36
	v_add_f32_e32 v33, 1.0, v33
	v_fma_f32 v35, -v34, v34, 1.0
	v_rcp_f32_e32 v33, v33
	v_sqrt_f32_e32 v35, v35
	v_add_f32_e32 v32, 1.0, v32
	v_rcp_f32_e32 v32, v32
	v_lshlrev_b32_e32 v36, 16, v157
	v_mul_f32_e32 v33, v35, v33
	v_mul_f32_e32 v174, v33, v36
	v_mul_f32_e32 v32, v138, v32
	v_fmac_f32_e32 v174, v34, v173
	v_exp_f32_e32 v33, v52
	v_mul_f32_e32 v52, v34, v51
	v_exp_f32_e32 v32, v32
	v_exp_f32_e32 v34, v37
	v_add_f32_e32 v33, 1.0, v33
	v_rcp_f32_e32 v33, v33
	v_fma_f32 v35, -v32, v32, 1.0
	v_add_f32_e32 v34, 1.0, v34
	v_sqrt_f32_e32 v35, v35
	v_rcp_f32_e32 v34, v34
	v_lshlrev_b32_e32 v36, 16, v196
	v_mul_f32_e32 v33, v35, v33
	v_mul_f32_e32 v34, v138, v34
	v_mul_f32_e32 v175, v33, v36
	v_exp_f32_e32 v33, v53
	v_exp_f32_e32 v34, v34
	v_fmac_f32_e32 v175, v32, v174
	v_mul_f32_e32 v53, v32, v52
	v_exp_f32_e32 v32, v38
	v_add_f32_e32 v33, 1.0, v33
	v_fma_f32 v35, -v34, v34, 1.0
	v_rcp_f32_e32 v33, v33
	v_sqrt_f32_e32 v35, v35
	v_add_f32_e32 v32, 1.0, v32
	v_rcp_f32_e32 v32, v32
	v_lshlrev_b32_e32 v36, 16, v197
	v_mul_f32_e32 v33, v35, v33
	v_mul_f32_e32 v176, v33, v36
	v_mul_f32_e32 v32, v138, v32
	v_fmac_f32_e32 v176, v34, v175
	v_exp_f32_e32 v33, v54
	v_mul_f32_e32 v54, v34, v53
	v_exp_f32_e32 v32, v32
	v_exp_f32_e32 v34, v39
	v_add_f32_e32 v33, 1.0, v33
	v_rcp_f32_e32 v33, v33
	v_fma_f32 v35, -v32, v32, 1.0
	v_add_f32_e32 v34, 1.0, v34
	v_sqrt_f32_e32 v35, v35
	v_rcp_f32_e32 v34, v34
	v_lshlrev_b32_e32 v36, 16, v177
	v_mul_f32_e32 v33, v35, v33
	v_mul_f32_e32 v34, v138, v34
	v_mul_f32_e32 v177, v33, v36
	v_exp_f32_e32 v33, v55
	v_exp_f32_e32 v34, v34
	v_fmac_f32_e32 v177, v32, v176
	v_mul_f32_e32 v55, v32, v54
	v_exp_f32_e32 v32, v40
	v_add_f32_e32 v33, 1.0, v33
	v_fma_f32 v35, -v34, v34, 1.0
	v_rcp_f32_e32 v33, v33
	v_sqrt_f32_e32 v35, v35
	v_add_f32_e32 v32, 1.0, v32
	v_rcp_f32_e32 v32, v32
	v_lshlrev_b32_e32 v36, 16, v178
	v_mul_f32_e32 v33, v35, v33
	v_mul_f32_e32 v178, v33, v36
	v_mul_f32_e32 v32, v138, v32
	v_fmac_f32_e32 v178, v34, v177
	v_exp_f32_e32 v33, v56
	v_mul_f32_e32 v56, v34, v55
	v_exp_f32_e32 v32, v32
	v_exp_f32_e32 v34, v41
	v_add_f32_e32 v33, 1.0, v33
	v_rcp_f32_e32 v33, v33
	v_fma_f32 v35, -v32, v32, 1.0
	v_add_f32_e32 v34, 1.0, v34
	v_sqrt_f32_e32 v35, v35
	v_rcp_f32_e32 v34, v34
	v_lshlrev_b32_e32 v36, 16, v179
	v_mul_f32_e32 v33, v35, v33
	v_mul_f32_e32 v34, v138, v34
	v_mul_f32_e32 v179, v33, v36
	v_exp_f32_e32 v33, v57
	v_exp_f32_e32 v34, v34
	v_fmac_f32_e32 v179, v32, v178
	v_mul_f32_e32 v57, v32, v56
	v_exp_f32_e32 v32, v42
	v_add_f32_e32 v33, 1.0, v33
	v_fma_f32 v35, -v34, v34, 1.0
	v_rcp_f32_e32 v33, v33
	v_sqrt_f32_e32 v35, v35
	v_add_f32_e32 v32, 1.0, v32
	v_rcp_f32_e32 v32, v32
	v_lshlrev_b32_e32 v36, 16, v180
	v_mul_f32_e32 v33, v35, v33
	v_mul_f32_e32 v180, v33, v36
	v_mul_f32_e32 v32, v138, v32
	v_fmac_f32_e32 v180, v34, v179
	v_exp_f32_e32 v33, v58
	v_mul_f32_e32 v58, v34, v57
	v_exp_f32_e32 v32, v32
	v_exp_f32_e32 v34, v43
	v_add_f32_e32 v33, 1.0, v33
	v_rcp_f32_e32 v33, v33
	v_fma_f32 v35, -v32, v32, 1.0
	v_add_f32_e32 v34, 1.0, v34
	v_sqrt_f32_e32 v35, v35
	v_rcp_f32_e32 v34, v34
	s_waitcnt lgkmcnt(13)
	v_lshlrev_b32_e32 v36, 16, v181
	v_mul_f32_e32 v33, v35, v33
	v_mul_f32_e32 v34, v138, v34
	v_mul_f32_e32 v181, v33, v36
	v_exp_f32_e32 v33, v59
	v_exp_f32_e32 v34, v34
	v_fmac_f32_e32 v181, v32, v180
	v_mul_f32_e32 v59, v32, v58
	v_exp_f32_e32 v32, v44
	v_add_f32_e32 v33, 1.0, v33
	v_fma_f32 v35, -v34, v34, 1.0
	v_rcp_f32_e32 v33, v33
	v_sqrt_f32_e32 v35, v35
	v_add_f32_e32 v32, 1.0, v32
	v_rcp_f32_e32 v32, v32
	s_waitcnt lgkmcnt(12)
	v_lshlrev_b32_e32 v36, 16, v182
	v_mul_f32_e32 v33, v35, v33
	v_mul_f32_e32 v182, v33, v36
	v_mul_f32_e32 v32, v138, v32
	v_fmac_f32_e32 v182, v34, v181
	v_exp_f32_e32 v33, v60
	v_mul_f32_e32 v60, v34, v59
	v_exp_f32_e32 v32, v32
	v_exp_f32_e32 v34, v45
	v_add_f32_e32 v33, 1.0, v33
	v_rcp_f32_e32 v33, v33
	v_fma_f32 v35, -v32, v32, 1.0
	v_add_f32_e32 v34, 1.0, v34
	v_sqrt_f32_e32 v35, v35
	v_rcp_f32_e32 v34, v34
	s_waitcnt lgkmcnt(11)
	v_lshlrev_b32_e32 v36, 16, v183
	v_mul_f32_e32 v33, v35, v33
	v_mul_f32_e32 v34, v138, v34
	v_mul_f32_e32 v183, v33, v36
	v_exp_f32_e32 v33, v61
	v_exp_f32_e32 v34, v34
	v_fmac_f32_e32 v183, v32, v182
	v_mul_f32_e32 v61, v32, v60
	v_exp_f32_e32 v32, v46
	v_add_f32_e32 v33, 1.0, v33
	v_fma_f32 v35, -v34, v34, 1.0
	v_rcp_f32_e32 v33, v33
	v_sqrt_f32_e32 v35, v35
	v_add_f32_e32 v32, 1.0, v32
	v_rcp_f32_e32 v32, v32
	s_waitcnt lgkmcnt(10)
	v_lshlrev_b32_e32 v36, 16, v184
	v_mul_f32_e32 v33, v35, v33
	v_mul_f32_e32 v184, v33, v36
	v_fmac_f32_e32 v184, v34, v183
	v_exp_f32_e32 v33, v62
	v_mul_f32_e32 v62, v34, v61
	v_mul_f32_e32 v32, v138, v32
	v_exp_f32_e32 v34, v47
	v_exp_f32_e32 v32, v32
	v_add_f32_e32 v33, 1.0, v33
	v_rcp_f32_e32 v33, v33
	v_add_f32_e32 v34, 1.0, v34
	v_fma_f32 v35, -v32, v32, 1.0
	v_rcp_f32_e32 v34, v34
	v_sqrt_f32_e32 v35, v35
	s_waitcnt lgkmcnt(9)
	v_lshlrev_b32_e32 v36, 16, v185
	v_mul_f32_e32 v186, v32, v62
	v_mul_f32_e32 v34, v138, v34
	v_mul_f32_e32 v33, v35, v33
	v_exp_f32_e32 v35, v63
	v_exp_f32_e32 v34, v34
	v_mul_f32_e32 v63, v33, v36
	v_fmac_f32_e32 v63, v32, v184
	v_add_f32_e32 v33, 1.0, v35
	v_fma_f32 v35, -v34, v34, 1.0
	v_rcp_f32_e32 v33, v33
	v_sqrt_f32_e32 v35, v35
	s_waitcnt lgkmcnt(8)
	v_lshlrev_b32_e32 v32, 16, v187
	v_mul_f32_e32 v187, v34, v186
	v_mul_f32_e32 v33, v35, v33
	v_mul_f32_e32 v185, v33, v32
	v_and_b32_e32 v33, 64, v153
	v_xor_b32_e32 v32, 32, v153
	v_add_u32_e32 v33, 64, v33
	v_cmp_lt_i32_e64 s[18:19], v32, v33
	v_fmac_f32_e32 v185, v34, v63
	s_nop 0
	v_cndmask_b32_e64 v32, v153, v32, s[18:19]
	v_lshlrev_b32_e32 v157, 2, v32
	ds_bpermute_b32 v188, v157, v187
	ds_bpermute_b32 v189, v157, v185
	s_and_saveexec_b64 s[18:19], vcc
	s_cbranch_execz .LBB0_299
	s_waitcnt lgkmcnt(0)
	v_fma_f32 v32, v188, v185, v189
	v_mul_f32_e32 v33, v187, v188
	ds_write2_b32 v147, v33, v32 offset1:32

;     __device__ __forceinline__ void fused(f32x4 (&acc)[2][2][4][2], const Unit& u, int wr, int wc, int fr, int fq, LAS unsigned char* lds, int wid, int lane) const {
;     ...
;         const int row0 = u.pm * BM + wr * 64 + fr, col0 = u.pn * BM + wc * 32 + 4 * fq, b = u.pm >> 3;
;         f32x4 gv[2][2];
; #pragma unroll
;         for (int bj = 0; bj < 2; ++bj)
; #pragma unroll
;             for (int n = 0; n < 2; ++n) gv[bj][n] = *(const f32x4*)(ada + b * 3072 + 2048 + col0 + bj * HALF + n * 16);
; #pragma unroll
;         for (int ai = 0; ai < 2; ++ai)
; #pragma unroll
;             for (int m = 0; m < 4; ++m) { const int row = row0 + ai * HALF + m * 16; const size_t off = (size_t)row * DM + col0; float ss = 0.f;
; #pragma unroll
;                 for (int bj = 0; bj < 2; ++bj)
; #pragma unroll
;                     for (int n = 0; n < 2; ++n) { const f32x4 xv = *(const f32x4*)(x + off + bj * HALF + n * 16); const f32x4 o = xv + gv[bj][n] * acc[ai][bj][m][n];
;                         acc[ai][bj][m][n] = o; ss += (o[0] * o[0] + o[1] * o[1]) + (o[2] * o[2] + o[3] * o[3]); }
;                 ss += __shfl_xor(ss, 16); ss += __shfl_xor(ss, 32);
;                 if (fq == 0) Pq[(ai * HALF + wr * 64 + m * 16 + fr) * 4 + wc] = ss; }
.LBB0_435:
	s_lshl_b32 s0, s15, 5
	s_lshl_b32 s1, s16, 8
	s_or_b32 s0, s1, s0
	v_lshrrev_b32_e32 v128, 2, v150
	v_and_or_b32 v146, v128, 12, s0
	s_lshr_b32 s0, s14, 3
	s_mulk_i32 s0, 0xc00
	s_lshl_b32 s2, s14, 8
	s_ashr_i32 s1, s0, 31
	s_add_i32 s3, s2, s57
	s_lshl_b64 s[0:1], s[0:1], 2
	s_add_u32 s0, s22, s0
	v_ashrrev_i32_e32 v147, 31, v146
	s_addc_u32 s1, s23, s1
	v_lshlrev_b64 v[144:145], 2, v[146:147]
	v_lshl_add_u64 v[128:129], s[0:1], 0, v[144:145]
	s_mov_b64 s[0:1], 0x2000
	v_lshl_add_u64 v[140:141], v[128:129], 0, s[0:1]
	s_movk_i32 s0, 0x2000
	v_or_b32_e32 v148, s3, v148
	v_add_co_u32_e32 v128, vcc, s0, v128
	v_ashrrev_i32_e32 v149, 31, v148
	s_nop 0
	v_addc_co_u32_e32 v129, vcc, 0, v129, vcc
	v_lshlrev_b64 v[132:133], 12, v[148:149]
	s_barrier
	global_load_dwordx4 v[128:131], v[128:129], off
	v_lshl_add_u64 v[132:133], s[36:37], 0, v[132:133]
	v_lshl_add_u64 v[232:233], v[132:133], 0, v[144:145]
	global_load_dwordx4 v[136:139], v[140:141], off offset:64
	global_load_dwordx4 v[132:135], v[140:141], off offset:512
	global_load_dwordx4 v[140:143], v[140:141], off offset:576
	global_load_dwordx4 v[168:171], v[232:233], off
	global_load_dwordx4 v[172:175], v[232:233], off offset:64
	global_load_dwordx4 v[176:179], v[232:233], off offset:512
	global_load_dwordx4 v[180:183], v[232:233], off offset:576
	s_mov_b64 s[4:5], 0x10000
	v_lshl_add_u64 v[234:235], v[232:233], 0, s[4:5]
	global_load_dwordx4 v[184:187], v[234:235], off
	global_load_dwordx4 v[188:191], v[234:235], off offset:64
	global_load_dwordx4 v[192:195], v[234:235], off offset:512
	global_load_dwordx4 v[196:199], v[234:235], off offset:576
	s_mov_b64 s[4:5], 0x20000
	v_lshl_add_u64 v[234:235], v[232:233], 0, s[4:5]
	global_load_dwordx4 v[200:203], v[234:235], off
	global_load_dwordx4 v[204:207], v[234:235], off offset:64
	global_load_dwordx4 v[208:211], v[234:235], off offset:512
	global_load_dwordx4 v[212:215], v[234:235], off offset:576
	s_mov_b64 s[4:5], 0x30000
	v_lshl_add_u64 v[234:235], v[232:233], 0, s[4:5]
	global_load_dwordx4 v[216:219], v[234:235], off
	global_load_dwordx4 v[220:223], v[234:235], off offset:64
	global_load_dwordx4 v[224:227], v[234:235], off offset:512
	global_load_dwordx4 v[228:231], v[234:235], off offset:576
	v_and_b32_e32 v154, 63, v150
	v_mbcnt_lo_u32_b32 v150, -1, 0
	v_mbcnt_hi_u32_b32 v150, -1, v150
	v_and_b32_e32 v153, 64, v150
	v_xor_b32_e32 v151, 16, v150
	v_add_u32_e32 v153, 64, v153
	v_cmp_lt_i32_e32 vcc, v151, v153
	s_lshl_b32 s3, s15, 2
	s_add_i32 s3, s3, 0
	v_cndmask_b32_e32 v151, v150, v151, vcc
	v_lshlrev_b32_e32 v155, 2, v151
	v_cmp_gt_u32_e64 s[0:1], 16, v154
	v_xor_b32_e32 v157, 32, v150
	v_cmp_lt_i32_e32 vcc, v157, v153
	s_nop 1
	v_cndmask_b32_e32 v150, v150, v157, vcc
	v_lshlrev_b32_e32 v157, 2, v150
	v_lshl_add_u32 v156, v152, 4, s3
	s_waitcnt vmcnt(12)
	v_pk_fma_f32 v[124:125], v[124:125], v[128:129], v[168:169]
	v_pk_fma_f32 v[126:127], v[126:127], v[130:131], v[170:171]
	v_pk_fma_f32 v[120:121], v[120:121], v[136:137], v[172:173]
	v_pk_fma_f32 v[122:123], v[122:123], v[138:139], v[174:175]
	v_pk_fma_f32 v[116:117], v[116:117], v[132:133], v[176:177]
	v_pk_fma_f32 v[118:119], v[118:119], v[134:135], v[178:179]
	v_pk_fma_f32 v[112:113], v[112:113], v[140:141], v[180:181]
	v_pk_fma_f32 v[114:115], v[114:115], v[142:143], v[182:183]
	s_mov_b64 s[4:5], 0x80000
	v_lshl_add_u64 v[234:235], v[232:233], 0, s[4:5]
	global_load_dwordx4 v[168:171], v[234:235], off
	global_load_dwordx4 v[172:175], v[234:235], off offset:64
	global_load_dwordx4 v[176:179], v[234:235], off offset:512
	global_load_dwordx4 v[180:183], v[234:235], off offset:576
	v_mul_f32_e32 v240, v125, v125
	v_fmac_f32_e32 v240, v124, v124
	v_mul_f32_e32 v248, v127, v127
	v_fmac_f32_e32 v248, v126, v126
	v_mul_f32_e32 v249, v121, v121
	v_fmac_f32_e32 v249, v120, v120
	v_mul_f32_e32 v250, v123, v123
	v_fmac_f32_e32 v250, v122, v122
	v_mul_f32_e32 v251, v117, v117
	v_fmac_f32_e32 v251, v116, v116
	v_mul_f32_e32 v252, v119, v119
	v_fmac_f32_e32 v252, v118, v118
	v_mul_f32_e32 v253, v113, v113
	v_fmac_f32_e32 v253, v112, v112
	v_mul_f32_e32 v254, v115, v115
	v_fmac_f32_e32 v254, v114, v114
	v_add_f32_e32 v240, v240, v248
	v_add_f32_e32 v249, v249, v250
	v_add_f32_e32 v251, v251, v252
	v_add_f32_e32 v240, v240, v249
	v_add_f32_e32 v240, v240, v251
	v_add_f32_e32 v253, v253, v254
	v_add_f32_e32 v240, v240, v253
	s_waitcnt vmcnt(12)
	v_pk_fma_f32 v[108:109], v[108:109], v[128:129], v[184:185]
	v_pk_fma_f32 v[110:111], v[110:111], v[130:131], v[186:187]
	v_pk_fma_f32 v[104:105], v[104:105], v[136:137], v[188:189]
	v_pk_fma_f32 v[106:107], v[106:107], v[138:139], v[190:191]
	v_pk_fma_f32 v[100:101], v[100:101], v[132:133], v[192:193]
	v_pk_fma_f32 v[102:103], v[102:103], v[134:135], v[194:195]
	v_pk_fma_f32 v[96:97], v[96:97], v[140:141], v[196:197]
	v_pk_fma_f32 v[98:99], v[98:99], v[142:143], v[198:199]
	s_mov_b64 s[4:5], 0x90000
	v_lshl_add_u64 v[234:235], v[232:233], 0, s[4:5]
	global_load_dwordx4 v[184:187], v[234:235], off
	global_load_dwordx4 v[188:191], v[234:235], off offset:64
	global_load_dwordx4 v[192:195], v[234:235], off offset:512
	global_load_dwordx4 v[196:199], v[234:235], off offset:576
	v_mul_f32_e32 v241, v109, v109
	v_fmac_f32_e32 v241, v108, v108
	v_mul_f32_e32 v248, v111, v111
	v_fmac_f32_e32 v248, v110, v110
	v_mul_f32_e32 v249, v105, v105
	v_fmac_f32_e32 v249, v104, v104
	v_mul_f32_e32 v250, v107, v107
	v_fmac_f32_e32 v250, v106, v106
	v_mul_f32_e32 v251, v101, v101
	v_fmac_f32_e32 v251, v100, v100
	v_mul_f32_e32 v252, v103, v103
	v_fmac_f32_e32 v252, v102, v102
	v_mul_f32_e32 v253, v97, v97
	v_fmac_f32_e32 v253, v96, v96
	v_mul_f32_e32 v254, v99, v99
	v_fmac_f32_e32 v254, v98, v98
	v_add_f32_e32 v241, v241, v248
	v_add_f32_e32 v249, v249, v250
	v_add_f32_e32 v251, v251, v252
	v_add_f32_e32 v241, v241, v249
	v_add_f32_e32 v241, v241, v251
	v_add_f32_e32 v253, v253, v254
	v_add_f32_e32 v241, v241, v253
	s_waitcnt vmcnt(12)
;     __device__ __forceinline__ void fused(f32x4 (&acc)[2][2][4][2], const Unit& u, int wr, int wc, int fr, int fq, LAS unsigned char* lds, int wid, int lane) const {
;     ...
;             for (int m = 0; m < 4; ++m) { const int row = row0 + ai * HALF + m * 16; const size_t off = (size_t)row * DM + col0; float ss = 0.f;
; #pragma unroll
;                 for (int bj = 0; bj < 2; ++bj)
; #pragma unroll
;                     for (int n = 0; n < 2; ++n) { const f32x4 xv = *(const f32x4*)(x + off + bj * HALF + n * 16); const f32x4 o = xv + gv[bj][n] * acc[ai][bj][m][n];
;                         acc[ai][bj][m][n] = o; ss += (o[0] * o[0] + o[1] * o[1]) + (o[2] * o[2] + o[3] * o[3]); }
;                 ss += __shfl_xor(ss, 16); ss += __shfl_xor(ss, 32);
;                 if (fq == 0) Pq[(ai * HALF + wr * 64 + m * 16 + fr) * 4 + wc] = ss; }
	v_pk_fma_f32 v[92:93], v[92:93], v[128:129], v[200:201]
	v_pk_fma_f32 v[94:95], v[94:95], v[130:131], v[202:203]
	v_pk_fma_f32 v[88:89], v[88:89], v[136:137], v[204:205]
	v_pk_fma_f32 v[90:91], v[90:91], v[138:139], v[206:207]
	v_pk_fma_f32 v[84:85], v[84:85], v[132:133], v[208:209]
	v_pk_fma_f32 v[86:87], v[86:87], v[134:135], v[210:211]
	v_pk_fma_f32 v[80:81], v[80:81], v[140:141], v[212:213]
	v_pk_fma_f32 v[82:83], v[82:83], v[142:143], v[214:215]
	s_mov_b64 s[4:5], 0xa0000
	v_lshl_add_u64 v[234:235], v[232:233], 0, s[4:5]
	global_load_dwordx4 v[200:203], v[234:235], off
	global_load_dwordx4 v[204:207], v[234:235], off offset:64
	global_load_dwordx4 v[208:211], v[234:235], off offset:512
	global_load_dwordx4 v[212:215], v[234:235], off offset:576
	v_mul_f32_e32 v242, v93, v93
	v_fmac_f32_e32 v242, v92, v92
	v_mul_f32_e32 v248, v95, v95
	v_fmac_f32_e32 v248, v94, v94
	v_mul_f32_e32 v249, v89, v89
	v_fmac_f32_e32 v249, v88, v88
	v_mul_f32_e32 v250, v91, v91
	v_fmac_f32_e32 v250, v90, v90
	v_mul_f32_e32 v251, v85, v85
	v_fmac_f32_e32 v251, v84, v84
	v_mul_f32_e32 v252, v87, v87
	v_fmac_f32_e32 v252, v86, v86
	v_mul_f32_e32 v253, v81, v81
	v_fmac_f32_e32 v253, v80, v80
	v_mul_f32_e32 v254, v83, v83
	v_fmac_f32_e32 v254, v82, v82
	v_add_f32_e32 v242, v242, v248
	v_add_f32_e32 v249, v249, v250
	v_add_f32_e32 v251, v251, v252
	v_add_f32_e32 v242, v242, v249
	v_add_f32_e32 v242, v242, v251
	v_add_f32_e32 v253, v253, v254
	v_add_f32_e32 v242, v242, v253
	s_waitcnt vmcnt(12)
	v_pk_fma_f32 v[76:77], v[76:77], v[128:129], v[216:217]
	v_pk_fma_f32 v[78:79], v[78:79], v[130:131], v[218:219]
	v_pk_fma_f32 v[72:73], v[72:73], v[136:137], v[220:221]
	v_pk_fma_f32 v[74:75], v[74:75], v[138:139], v[222:223]
	v_pk_fma_f32 v[68:69], v[68:69], v[132:133], v[224:225]
	v_pk_fma_f32 v[70:71], v[70:71], v[134:135], v[226:227]
	v_pk_fma_f32 v[64:65], v[64:65], v[140:141], v[228:229]
	v_pk_fma_f32 v[66:67], v[66:67], v[142:143], v[230:231]
	s_mov_b64 s[4:5], 0xb0000
	v_lshl_add_u64 v[234:235], v[232:233], 0, s[4:5]
	global_load_dwordx4 v[216:219], v[234:235], off
	global_load_dwordx4 v[220:223], v[234:235], off offset:64
	global_load_dwordx4 v[224:227], v[234:235], off offset:512
	global_load_dwordx4 v[228:231], v[234:235], off offset:576
	v_mul_f32_e32 v243, v77, v77
	v_fmac_f32_e32 v243, v76, v76
	v_mul_f32_e32 v248, v79, v79
	v_fmac_f32_e32 v248, v78, v78
	v_mul_f32_e32 v249, v73, v73
	v_fmac_f32_e32 v249, v72, v72
	v_mul_f32_e32 v250, v75, v75
	v_fmac_f32_e32 v250, v74, v74
	v_mul_f32_e32 v251, v69, v69
	v_fmac_f32_e32 v251, v68, v68
	v_mul_f32_e32 v252, v71, v71
	v_fmac_f32_e32 v252, v70, v70
	v_mul_f32_e32 v253, v65, v65
	v_fmac_f32_e32 v253, v64, v64
	v_mul_f32_e32 v254, v67, v67
	v_fmac_f32_e32 v254, v66, v66
	v_add_f32_e32 v243, v243, v248
	v_add_f32_e32 v249, v249, v250
	v_add_f32_e32 v251, v251, v252
	v_add_f32_e32 v243, v243, v249
	v_add_f32_e32 v243, v243, v251
	v_add_f32_e32 v253, v253, v254
	v_add_f32_e32 v243, v243, v253
	s_waitcnt vmcnt(12)
	v_pk_fma_f32 v[60:61], v[60:61], v[128:129], v[168:169]
	v_pk_fma_f32 v[62:63], v[62:63], v[130:131], v[170:171]
	v_pk_fma_f32 v[56:57], v[56:57], v[136:137], v[172:173]
	v_pk_fma_f32 v[58:59], v[58:59], v[138:139], v[174:175]
	v_pk_fma_f32 v[52:53], v[52:53], v[132:133], v[176:177]
	v_pk_fma_f32 v[54:55], v[54:55], v[134:135], v[178:179]
	v_pk_fma_f32 v[48:49], v[48:49], v[140:141], v[180:181]
	v_pk_fma_f32 v[50:51], v[50:51], v[142:143], v[182:183]
	v_mul_f32_e32 v244, v61, v61
	v_fmac_f32_e32 v244, v60, v60
	v_mul_f32_e32 v248, v63, v63
	v_fmac_f32_e32 v248, v62, v62
	v_mul_f32_e32 v249, v57, v57
	v_fmac_f32_e32 v249, v56, v56
	v_mul_f32_e32 v250, v59, v59
	v_fmac_f32_e32 v250, v58, v58
	v_mul_f32_e32 v251, v53, v53
	v_fmac_f32_e32 v251, v52, v52
	v_mul_f32_e32 v252, v55, v55
	v_fmac_f32_e32 v252, v54, v54
	v_mul_f32_e32 v253, v49, v49
	v_fmac_f32_e32 v253, v48, v48
	v_mul_f32_e32 v254, v51, v51
	v_fmac_f32_e32 v254, v50, v50
	v_add_f32_e32 v244, v244, v248
	v_add_f32_e32 v249, v249, v250
	v_add_f32_e32 v251, v251, v252
	v_add_f32_e32 v244, v244, v249
	v_add_f32_e32 v244, v244, v251
	v_add_f32_e32 v253, v253, v254
	v_add_f32_e32 v244, v244, v253
	s_waitcnt vmcnt(8)
;     __device__ __forceinline__ void fused(f32x4 (&acc)[2][2][4][2], const Unit& u, int wr, int wc, int fr, int fq, LAS unsigned char* lds, int wid, int lane) const {
;     ...
;             for (int m = 0; m < 4; ++m) { const int row = row0 + ai * HALF + m * 16; const size_t off = (size_t)row * DM + col0; float ss = 0.f;
; #pragma unroll
;                 for (int bj = 0; bj < 2; ++bj)
; #pragma unroll
;                     for (int n = 0; n < 2; ++n) { const f32x4 xv = *(const f32x4*)(x + off + bj * HALF + n * 16); const f32x4 o = xv + gv[bj][n] * acc[ai][bj][m][n];
;                         acc[ai][bj][m][n] = o; ss += (o[0] * o[0] + o[1] * o[1]) + (o[2] * o[2] + o[3] * o[3]); }
;                 ss += __shfl_xor(ss, 16); ss += __shfl_xor(ss, 32);
;                 if (fq == 0) Pq[(ai * HALF + wr * 64 + m * 16 + fr) * 4 + wc] = ss; }
	v_pk_fma_f32 v[44:45], v[44:45], v[128:129], v[184:185]
	v_pk_fma_f32 v[46:47], v[46:47], v[130:131], v[186:187]
	v_pk_fma_f32 v[40:41], v[40:41], v[136:137], v[188:189]
	v_pk_fma_f32 v[42:43], v[42:43], v[138:139], v[190:191]
	v_pk_fma_f32 v[36:37], v[36:37], v[132:133], v[192:193]
	v_pk_fma_f32 v[38:39], v[38:39], v[134:135], v[194:195]
	v_pk_fma_f32 v[32:33], v[32:33], v[140:141], v[196:197]
	v_pk_fma_f32 v[34:35], v[34:35], v[142:143], v[198:199]
	v_mul_f32_e32 v245, v45, v45
	v_fmac_f32_e32 v245, v44, v44
	v_mul_f32_e32 v248, v47, v47
	v_fmac_f32_e32 v248, v46, v46
	v_mul_f32_e32 v249, v41, v41
	v_fmac_f32_e32 v249, v40, v40
	v_mul_f32_e32 v250, v43, v43
	v_fmac_f32_e32 v250, v42, v42
	v_mul_f32_e32 v251, v37, v37
	v_fmac_f32_e32 v251, v36, v36
	v_mul_f32_e32 v252, v39, v39
	v_fmac_f32_e32 v252, v38, v38
	v_mul_f32_e32 v253, v33, v33
	v_fmac_f32_e32 v253, v32, v32
	v_mul_f32_e32 v254, v35, v35
	v_fmac_f32_e32 v254, v34, v34
	v_add_f32_e32 v245, v245, v248
	v_add_f32_e32 v249, v249, v250
	v_add_f32_e32 v251, v251, v252
	v_add_f32_e32 v245, v245, v249
	v_add_f32_e32 v245, v245, v251
	v_add_f32_e32 v253, v253, v254
	v_add_f32_e32 v245, v245, v253
	s_waitcnt vmcnt(4)
	v_pk_fma_f32 v[28:29], v[28:29], v[128:129], v[200:201]
	v_pk_fma_f32 v[30:31], v[30:31], v[130:131], v[202:203]
	v_pk_fma_f32 v[24:25], v[24:25], v[136:137], v[204:205]
	v_pk_fma_f32 v[26:27], v[26:27], v[138:139], v[206:207]
	v_pk_fma_f32 v[20:21], v[20:21], v[132:133], v[208:209]
	v_pk_fma_f32 v[22:23], v[22:23], v[134:135], v[210:211]
	v_pk_fma_f32 v[16:17], v[16:17], v[140:141], v[212:213]
	v_pk_fma_f32 v[18:19], v[18:19], v[142:143], v[214:215]
	v_mul_f32_e32 v246, v29, v29
	v_fmac_f32_e32 v246, v28, v28
	v_mul_f32_e32 v248, v31, v31
	v_fmac_f32_e32 v248, v30, v30
	v_mul_f32_e32 v249, v25, v25
	v_fmac_f32_e32 v249, v24, v24
	v_mul_f32_e32 v250, v27, v27
	v_fmac_f32_e32 v250, v26, v26
	v_mul_f32_e32 v251, v21, v21
	v_fmac_f32_e32 v251, v20, v20
	v_mul_f32_e32 v252, v23, v23
	v_fmac_f32_e32 v252, v22, v22
	v_mul_f32_e32 v253, v17, v17
	v_fmac_f32_e32 v253, v16, v16
	v_mul_f32_e32 v254, v19, v19
	v_fmac_f32_e32 v254, v18, v18
	v_add_f32_e32 v246, v246, v248
	v_add_f32_e32 v249, v249, v250
	v_add_f32_e32 v251, v251, v252
	v_add_f32_e32 v246, v246, v249
	v_add_f32_e32 v246, v246, v251
	v_add_f32_e32 v253, v253, v254
	v_add_f32_e32 v246, v246, v253
	s_waitcnt vmcnt(0)
	v_pk_fma_f32 v[148:149], v[12:13], v[128:129], v[216:217]
	v_pk_fma_f32 v[146:147], v[14:15], v[130:131], v[218:219]
	v_pk_fma_f32 v[136:137], v[8:9], v[136:137], v[220:221]
	v_pk_fma_f32 v[138:139], v[10:11], v[138:139], v[222:223]
	v_pk_fma_f32 v[132:133], v[4:5], v[132:133], v[224:225]
	v_pk_fma_f32 v[134:135], v[6:7], v[134:135], v[226:227]
	v_pk_fma_f32 v[130:131], v[0:1], v[140:141], v[228:229]
	v_pk_fma_f32 v[128:129], v[2:3], v[142:143], v[230:231]
	v_mul_f32_e32 v247, v149, v149
	v_fmac_f32_e32 v247, v148, v148
	v_mul_f32_e32 v248, v147, v147
	v_fmac_f32_e32 v248, v146, v146
	v_mul_f32_e32 v249, v137, v137
	v_fmac_f32_e32 v249, v136, v136
	v_mul_f32_e32 v250, v139, v139
	v_fmac_f32_e32 v250, v138, v138
	v_mul_f32_e32 v251, v133, v133
	v_fmac_f32_e32 v251, v132, v132
	v_mul_f32_e32 v252, v135, v135
	v_fmac_f32_e32 v252, v134, v134
	v_mul_f32_e32 v253, v131, v131
	v_fmac_f32_e32 v253, v130, v130
	v_mul_f32_e32 v254, v129, v129
	v_fmac_f32_e32 v254, v128, v128
	v_add_f32_e32 v247, v247, v248
	v_add_f32_e32 v249, v249, v250
	v_add_f32_e32 v251, v251, v252
	v_add_f32_e32 v247, v247, v249
	v_add_f32_e32 v247, v247, v251
	v_add_f32_e32 v253, v253, v254
	v_add_f32_e32 v247, v247, v253
	ds_bpermute_b32 v168, v155, v240
	ds_bpermute_b32 v169, v155, v241
	ds_bpermute_b32 v170, v155, v242
	ds_bpermute_b32 v171, v155, v243
	ds_bpermute_b32 v172, v155, v244
	ds_bpermute_b32 v173, v155, v245
	ds_bpermute_b32 v174, v155, v246
	ds_bpermute_b32 v175, v155, v247
	s_waitcnt lgkmcnt(0)
	v_add_f32_e32 v240, v240, v168
	v_add_f32_e32 v241, v241, v169
	v_add_f32_e32 v242, v242, v170
	v_add_f32_e32 v243, v243, v171
	v_add_f32_e32 v244, v244, v172
	v_add_f32_e32 v245, v245, v173
	v_add_f32_e32 v246, v246, v174
	v_add_f32_e32 v247, v247, v175
	ds_bpermute_b32 v168, v157, v240
	ds_bpermute_b32 v169, v157, v241
	ds_bpermute_b32 v170, v157, v242
	ds_bpermute_b32 v171, v157, v243
	ds_bpermute_b32 v172, v157, v244
	ds_bpermute_b32 v173, v157, v245
	ds_bpermute_b32 v174, v157, v246
	ds_bpermute_b32 v175, v157, v247
	s_and_saveexec_b64 s[4:5], s[0:1]
	s_waitcnt lgkmcnt(0)
	v_add_f32_e32 v240, v240, v168
	ds_write_b32 v156, v240
	v_add_f32_e32 v241, v241, v169
	ds_write_b32 v156, v241 offset:256
	v_add_f32_e32 v242, v242, v170
	ds_write_b32 v156, v242 offset:512
	v_add_f32_e32 v243, v243, v171
	ds_write_b32 v156, v243 offset:768
	v_add_f32_e32 v244, v244, v172
	ds_write_b32 v156, v244 offset:2048
	v_add_f32_e32 v245, v245, v173
	ds_write_b32 v156, v245 offset:2304
	v_add_f32_e32 v246, v246, v174
	ds_write_b32 v156, v246 offset:2560
	v_add_f32_e32 v247, v247, v175
	ds_write_b32 v156, v247 offset:2816
	s_or_b64 exec, exec, s[4:5]
	v_add_u32_e32 v153, 0x80, v152
